# speedup vs baseline: 1.0920x; 1.0021x over previous
; __device__ __forceinline__ void phase_fox_cumsum(const Params& p) {
;   float* LF = (float*)(p.ws + OFF_LF);
;   const int lane = threadIdx.x & 63;
;   const int gw = blockIdx.x * 4 + (threadIdx.x >> 6), nw = gridDim.x * 4;
;   for (int seq = gw; seq < 128; seq += nw) {
;     float* base = LF + (long)seq * 4096 + lane * 64;
;     float s = 0.f;
;     for (int i = 0; i < 64; i += 4) { float4 v = *(const float4*)(base + i); s += v.x + v.y + v.z + v.w; }
;     float incl = s;
; #pragma unroll
;     for (int d = 1; d < 64; d <<= 1) { float o = __shfl_up(incl, d); if (lane >= d) incl += o; }
.LBB0_179:
	s_or_b64 exec, exec, s[4:5]
	s_cmp_lt_u32 s98, 0x100
	s_cbranch_scc1 .Lprio1_skip
	s_setprio 1
.Lprio1_skip:
	v_lshrrev_b32_e32 v0, 6, v140
	v_lshl_add_u32 v64, s96, 2, v0
	s_movk_i32 s0, 0x80
	v_cmp_gt_i32_e32 vcc, s0, v64
	v_mbcnt_lo_u32_b32 v156, -1, 0
	s_barrier
	s_and_saveexec_b64 s[18:19], vcc
	s_cbranch_execz .LBB0_182
	v_mbcnt_hi_u32_b32 v0, -1, v156
	v_and_b32_e32 v1, 64, v0
	v_add_u32_e32 v3, -1, v0
	v_cmp_lt_i32_e32 vcc, v3, v1
	v_ashrrev_i32_e32 v65, 31, v64
	v_readlane_b32 s0, v225, 2
	v_cndmask_b32_e32 v3, v3, v0, vcc
	v_lshlrev_b32_e32 v68, 2, v3
	v_add_u32_e32 v3, -2, v0
	v_cmp_lt_i32_e64 s[4:5], v3, v1
	v_and_b32_e32 v2, 63, v140
	v_readlane_b32 s1, v225, 3
	v_cndmask_b32_e64 v3, v3, v0, s[4:5]
	v_lshlrev_b32_e32 v69, 2, v3
	v_add_u32_e32 v3, -4, v0
	v_cmp_lt_i32_e64 s[6:7], v3, v1
	s_lshl_b32 s20, s0, 2
	s_mov_b64 s[0:1], 0x3b740000
	v_cndmask_b32_e64 v3, v3, v0, s[6:7]
	v_lshlrev_b32_e32 v70, 2, v3
	v_add_u32_e32 v3, -8, v0
	v_cmp_lt_i32_e64 s[8:9], v3, v1
	s_ashr_i32 s21, s20, 31
	v_cmp_eq_u32_e32 vcc, 0, v2
	v_cndmask_b32_e64 v3, v3, v0, s[8:9]
	v_lshlrev_b32_e32 v71, 2, v3
	v_add_u32_e32 v3, -16, v0
	v_cmp_lt_i32_e64 s[10:11], v3, v1
	v_cmp_gt_u32_e64 s[4:5], 2, v2
	v_cmp_gt_u32_e64 s[6:7], 4, v2
	v_cndmask_b32_e64 v3, v3, v0, s[10:11]
	v_lshlrev_b32_e32 v72, 2, v3
	v_subrev_u32_e32 v3, 32, v0
	v_cmp_lt_i32_e64 s[12:13], v3, v1
	v_cmp_gt_u32_e64 s[8:9], 8, v2
	v_cmp_gt_u32_e64 s[10:11], 16, v2
	v_cndmask_b32_e64 v0, v3, v0, s[12:13]
	v_lshlrev_b32_e32 v73, 2, v0
	v_lshlrev_b64 v[0:1], 14, v[64:65]
	v_lshl_or_b32 v0, v2, 8, v0
	v_lshl_add_u64 v[0:1], s[30:31], 0, v[0:1]
	v_cmp_gt_u32_e64 s[12:13], 32, v2
	v_lshl_add_u64 v[66:67], v[0:1], 0, s[0:1]
	s_lshl_b64 s[22:23], s[20:21], 14
	s_mov_b64 s[26:27], 0
	s_movk_i32 s0, 0x7f

; __device__ __forceinline__ ushort_t* wsb(const Params& p, size_t off) { return (ushort_t*)(p.ws + off); }
; __device__ __forceinline__ void phase_fox_attn(const Params& p, char* smem) {
;   const ushort_t* Qb = wsb(p, OFF_P + 0 * SLOT);
;   const ushort_t* Kb = wsb(p, OFF_P + 1 * SLOT);
;   const ushort_t* Vt = wsb(p, OFF_P + 2 * SLOT);
;   const ushort_t* G = wsb(p, OFF_P + 3 * SLOT);
;   ushort_t* M = wsb(p, OFF_P + 4 * SLOT);
;   const float* LF = (const float*)(p.ws + OFF_LF);
;   char* sKb = smem;
;   char* sVb = smem + 32768;
;   float* sC = (float*)(smem + 65536);
;   for (int item = blockIdx.x; item < 4096; item += gridDim.x) {
;     int tid = threadIdx.x;
;     asm volatile("" : "+v"(tid));
;     const int lane = tid & 63, wave = tid >> 6, lr = lane & 15, g = lane >> 4;
;     const int kbase = lr * 256 + ((g ^ lr) << 4);
;     const int vbase = lr * 128 + ((((g >> 1) ^ ((lr >> 1) & 7))) << 4) + (g & 1) * 8;
;     const int m_ = item >> 9, grp_ = (item >> 7) & 3;
;     const int qt = 31 - (4 * m_ + ((m_ & 1) ? 3 - grp_ : grp_)), bh = item & 127, b = bh >> 3, h = bh & 7;
;     const int q0 = qt * 128;
;     const long tokbase = (long)b * 4096;
;     const int nkv = 2 * (qt + 1);
;     const int krow = tid >> 4, kch = ((tid & 15) ^ ((tid >> 4) & 15)) * 8;
;     const int vrow = tid >> 3, vch = ((tid & 7) ^ ((tid >> 4) & 7)) * 8;
;     const ushort_t* ksrc = Kb + (tokbase + krow) * 1024 + h * 128 + kch;
;     const ushort_t* vsrc = Vt + ((long)bh * 128 + vrow) * 4096 + vch;
;     const float* csrc = LF + (long)bh * 4096 + lane;
.Lprio2_skip:
	s_add_u32 s22, s30, 0x8000000
	s_addc_u32 s23, s31, 0
	s_add_u32 s26, s30, 0x18000000
	s_addc_u32 s27, s31, 0
	s_add_u32 s42, s30, 0x20000000
	s_addc_u32 s43, s31, 0
	s_cmpk_gt_i32 s96, 0xfff
	s_barrier
	s_cbranch_scc1 .LBB0_205
	v_mbcnt_hi_u32_b32 v118, -1, v156
	v_and_b32_e32 v0, 64, v118
	s_mov_b32 s44, 0xfffe0000
	s_movk_i32 s54, 0xff80
	s_mov_b32 s56, 0xfffe8000
	s_mov_b32 s70, 0xffff0000
	s_movk_i32 s76, 0x8000
	s_movk_i32 s82, 0xff00
	s_mov_b32 s7, 0
	v_mov_b32_e32 v105, 0
	s_mov_b64 s[8:9], 0x8000
	s_mov_b64 s[10:11], 0x40000
	s_mov_b64 s[12:13], 0x10000
	s_mov_b64 s[14:15], 0x80000
	s_mov_b64 s[18:19], 0x18000
	s_mov_b64 s[20:21], 0xc0000
	v_xor_b32_e32 v119, 16, v118
	v_add_u32_e32 v120, 64, v0
	v_xor_b32_e32 v121, 32, v118
	s_mov_b32 s45, -1
	s_mov_b32 s55, -1
	s_mov_b32 s57, -1
	s_mov_b64 s[68:69], 0x3ff80
	s_mov_b32 s71, -1
	s_mov_b64 s[72:73], 0x7ff80
	s_mov_b32 s77, -1
	s_mov_b64 s[80:81], 0xbff80
	s_mov_b32 s83, -1
	s_mov_b32 s0, 0xff800000
	v_mov_b32_e32 v122, 0xff800000
	s_mov_b32 s1, s96
	s_branch .LBB0_196

; __device__ __forceinline__ ushort_t* wsb(const Params& p, size_t off) { return (ushort_t*)(p.ws + off); }
; __device__ __forceinline__ ushort_t* wts(const Params& p, size_t eoff) { return (ushort_t*)(p.ws + OFF_W) + eoff; }
; __device__ __forceinline__ int opaque_tid() { int t = threadIdx.x; asm volatile("" : "+v"(t)); return t; }
; template <bool MIX>
; __device__ __forceinline__ void phase_outproj_ln(const Params& p, int layer, const ushort_t* M, size_t w_out_off, char* smem) {
;   const float* xsrc = (layer == 0) ? p.in[I_X] : p.out;
;   float* out = p.out;
;   ushort_t* xb = wsb(p, OFF_XB);
;   const float* lg = p.in[I_LNG] + layer * 1024;
;   const float* lb = p.in[I_LNB] + layer * 1024;
;   float* Cs = (float*)smem;
;   float* sst = (float*)(smem + 73728);
;   for (int mt = blockIdx.x; mt < T_TOK / 128; mt += gridDim.x) {
;     const int tid = opaque_tid();
;     const int l32 = tid & 31, rgrp = tid >> 5;
;     const int row0 = mt * 128;
;     __syncthreads();
;     sst[tid] = 0.f;
;     f32x4 acc[8][4];
;     for (int nt = 0; nt < 8; ++nt) {
;       if ((nt & 1) == 0)
;         gemm_core256<false>(wts(p, w_out_off) + (long)(nt >> 1) * 256 * 1024, 1024, M + (long)row0 * 1024, 1024, 1024, smem, acc, 0, nullptr);
.Lprio3_skip:
	s_cmpk_lt_i32 s96, 0x200
	s_cselect_b64 s[0:1], -1, 0
	v_writelane_b32 v225, s0, 8
	s_cmpk_gt_i32 s96, 0x1ff
	s_barrier
	v_writelane_b32 v225, s1, 9
	s_cbranch_scc1 .LBB0_252
	s_add_u32 s0, s30, 0x38840000
	v_readlane_b32 s2, v225, 2
	s_addc_u32 s1, s31, 0
	s_lshl_b32 s6, s96, 7
	v_readlane_b32 s3, v225, 3
	s_lshl_b32 s2, s2, 7
	s_or_b32 s3, s6, 8
	s_add_u32 s8, s28, 8
	s_addc_u32 s9, s29, 0
	s_add_u32 s10, s36, 8
	s_addc_u32 s11, s37, 0
	v_mov_b32_e32 v1, 0
	s_movk_i32 s19, 0xf800
	s_mov_b64 s[12:13], 0x20000
	s_mov_b64 s[14:15], 0x20040
	s_mov_b64 s[16:17], 0x20020100
	s_movk_i32 s35, 0x84
	s_mov_b32 s18, 0x3fd744fd
	s_mov_b64 s[20:21], 0x10000
	s_mov_b64 s[54:55], 0x200
	s_mov_b32 s56, 0x3a800000
	s_mov_b32 s57, 0x800000
	v_mbcnt_hi_u32_b32 v143, -1, v156
	s_mov_b32 s84, s96
	s_mov_b64 s[68:69], 0x8000
	s_mov_b64 s[70:71], 0x100

; __device__ __forceinline__ ushort_t* wsb(const Params& p, size_t off) { return (ushort_t*)(p.ws + off); }
; __device__ __forceinline__ ushort_t* wts(const Params& p, size_t eoff) { return (ushort_t*)(p.ws + OFF_W) + eoff; }
; __device__ __forceinline__ int opaque_tid() { int t = threadIdx.x; asm volatile("" : "+v"(t)); return t; }
; #define TILE_LOOP2(NTV) for (int q_ = blockIdx.x >> 3, mt = 0, nt = 0; tile_coords(q_, (NTV), mt, nt, 256); q_ += gridDim.x >> 3)
; __device__ __forceinline__ void phase_dsa_inproj(const Params& p, char* smem) {
;   float* Cs = (float*)smem;
;   const ushort_t* xb = wsb(p, OFF_XB);
;   ushort_t* PB = wsb(p, OFF_P);
;   float* WI = (float*)(p.ws + OFF_WI);
;   const float* kvg = p.in[I_DSA_KVG];
;   const int NT = 24;
;   TILE_LOOP2(NT) {
;     int tid = threadIdx.x;
;     asm volatile("" : "+v"(tid));
;     const int row = tid >> 1, hf = tid & 1;
;     f32x4 acc[8][4];
;     gemm_core256<false>(xb + (long)mt * 256 * 1024, 1024, wts(p, W_DSA_IN) + (long)nt * 128 * 1024, 1024, 1024, smem, acc, 0, nullptr);
; #pragma unroll 1
;     for (int half = 0; half < 2; ++half) {
;     const int row0 = mt * 256 + half * 128;
;     if (((opaque_tid() >> 7) & 1) == half) stage_acc8(Cs, acc);
;     __syncthreads();
;     const long tok = row0 + row;
;     const float pos = (float)((row0 & 4095) + row);
;     float* cr = Cs + row * CS_LD;
;     const float* cs = cr + hf * 64;
;     if (nt < 8) {
;       store_tile(PB + DSA_QF + (long)row0 * 1280 + nt * 160, 1280, Cs, [](float v, int, int) { return v * QSCALE_F; });
;     } else if (nt < 10) {
; #pragma unroll 1
;       for (int hh = 0; hh < 2; ++hh) {
;         const int head = (nt - 8) * 4 + hf * 2 + hh;
;         const float* x = cs + hh * 32;
;         float o[32];
; #pragma unroll
;         for (int i = 0; i < 16; ++i) {
;           const float inv = __builtin_amdgcn_exp2f(-(float)i * (L2_THETA_A / 16.f));
;           float sn, c_;
;           __sincosf(pos * inv, &sn, &c_);
;           o[i] = (x[i] * c_ - x[i + 16] * sn) * QSCALE_F;
.Lprio4_skip:
	s_add_u32 s36, s30, 0x3b940000
	s_addc_u32 s37, s31, 0
	s_add_u32 s92, s30, 0xfc00000
	s_addc_u32 s3, s31, 0
	s_add_u32 s0, s30, 0xf400000
	s_addc_u32 s1, s31, 0
	s_add_u32 s56, s30, 0xa000000
	v_exp_f32_e32 v143, 0xbf9773da
	v_exp_f32_e32 v145, 0xc01773da
	v_exp_f32_e32 v207, 0xc0632dc7
	v_exp_f32_e32 v208, 0xc09773da
	v_exp_f32_e32 v209, 0xc0bd50d0
	v_exp_f32_e32 v210, 0xc0e32dc7
	v_exp_f32_e32 v211, 0xc104855f
	v_exp_f32_e32 v212, 0xc11773da
	v_exp_f32_e32 v213, 0xc12a6255
	v_exp_f32_e32 v214, 0xc13d50d0
	v_exp_f32_e32 v215, 0xc1503f4c
	v_exp_f32_e32 v216, 0xc1632dc7
	v_exp_f32_e32 v217, 0xc1761c42
	v_exp_f32_e32 v218, 0xc184855f
	v_exp_f32_e32 v219, 0xc18dfc9c
	v_writelane_b32 v225, s0, 6
	s_addc_u32 s57, s31, 0
	s_mov_b32 s7, 0
	v_writelane_b32 v225, s1, 7
	s_add_u32 s0, s30, 0x38a40000
	s_addc_u32 s1, s31, 0
	s_movk_i32 s13, 0xf800
	v_mov_b32_e32 v1, 0
	s_mov_b64 s[8:9], 0x20000
	s_mov_b64 s[10:11], 0x20040
	s_movk_i32 s15, 0x210
	s_mov_b32 s12, 0x3d3504f3
	s_movk_i32 s84, 0x140
	v_mov_b32_e32 v220, 0x358637bd
	s_movk_i32 s85, 0xa00
	s_mov_b32 s14, 0x3e0293ee
	v_mbcnt_hi_u32_b32 v206, -1, v156
	s_mov_b32 s18, s7
	s_mov_b32 s16, s7
	s_mov_b32 s88, s94
	s_barrier
	s_branch .LBB0_265

; __device__ __forceinline__ ushort_t* wsb(const Params& p, size_t off) { return (ushort_t*)(p.ws + off); }
; __device__ __forceinline__ void phase_dsa_attn(const Params& p, char* smem) {
;   const ushort_t* PB = wsb(p, OFF_P);
;   const ushort_t* QF = PB + DSA_QF;
;   const ushort_t* KVL = PB + DSA_KVL;
;   const ushort_t* QI = PB + DSA_QI;
;   const ushort_t* KI = PB + DSA_KI;
;   ushort_t* OL = wsb(p, OFF_P) + DSA_OL;
;   const float* WI = (const float*)(p.ws + OFF_WI);
;   ushort_t* sscore = (ushort_t*)smem;
;   ushort_t* sidx = (ushort_t*)(smem + 65536);
;   int* shist = (int*)(smem + 69632);
;   int* scnt = (int*)(smem + 73728);
;   char* sgat = smem;
;   for (int item = blockIdx.x; item < T_TOK / 8; item += gridDim.x) {
;     int tid = threadIdx.x;
;     asm volatile("" : "+v"(tid));
;     const int lane = tid & 63, wave = tid >> 6, lr = lane & 15, g = lane >> 4;
;     const int b = item >> 9, pidx = item & 511, t0 = ((b & 1) ? 511 - pidx : pidx) * 8;
;     const long tokb = (long)b * 4096;
.Lprio5_skip:
	s_add_u32 s50, s30, 0x17c00000
	s_addc_u32 s51, s31, 0
	s_cmpk_gt_i32 s96, 0x1fff
	s_barrier
	v_writelane_b32 v225, s95, 16
	s_cbranch_scc1 .LBB0_390
	s_add_u32 s68, s30, 0xb400000
	s_addc_u32 s69, s31, 0
	s_add_u32 s70, s30, 0xf402000
	v_writelane_b32 v225, s92, 10
	s_addc_u32 s71, s31, 0
	s_mov_b32 s0, 0
	v_mov_b32_e32 v101, 0
	s_add_i32 s1, 0, 0x11000
	s_movk_i32 s2, 0xff
	v_mov_b32_e32 v128, 1
	s_movk_i32 s84, 0x100
	s_movk_i32 s85, 0x150
	s_mov_b32 s88, 0xccccccd
	s_movk_i32 s89, 0xffec
	s_movk_i32 s90, 0x140
	s_add_i32 s91, 0, 0x10040
	s_movk_i32 s92, 0xa00
	s_mov_b32 s95, 0xff800000
	v_mov_b32_e32 v129, 0x80
	v_mov_b32_e32 v130, 0xff800000
	s_branch .LBB0_330

; __device__ __forceinline__ ushort_t* wsb(const Params& p, size_t off) { return (ushort_t*)(p.ws + off); }
; __device__ __forceinline__ ushort_t* wts(const Params& p, size_t eoff) { return (ushort_t*)(p.ws + OFF_W) + eoff; }
; #define TILE_LOOP(NTV) for (int q_ = blockIdx.x >> 3, mt = 0, nt = 0; tile_coords(q_, (NTV), mt, nt); q_ += gridDim.x >> 3)
; __device__ __forceinline__ void phase_dsa_uv(const Params& p, char* smem) {
;   float* Cs = (float*)smem;
;   const ushort_t* PB = wsb(p, OFF_P);
;   ushort_t* M = wsb(p, OFF_P) + DSA_M;
;   TILE_LOOP(8) {
;     int tid = threadIdx.x;
;     asm volatile("" : "+v"(tid));
;     const int row = tid >> 1, hf = tid & 1;
;     const int h = nt, row0 = mt * 128;
;     f32x4 acc[4][4];
;     gemm_core<false, false>(PB + DSA_OL + (long)row0 * 1024 + h * 128, 1024, wts(p, W_DSA_UV) + (long)h * 128 * 128, 128, 128, smem, acc);
.Lprio6_skip:
	s_add_u32 s0, s30, 0x1fc00000
	s_addc_u32 s1, s31, 0
	s_cmpk_gt_u32 s96, 0xfff
	s_barrier
	s_cbranch_scc1 .LBB0_403
	s_lshr_b32 s2, s96, 6
	s_and_b32 s2, s2, 56
	s_or_b32 s2, s2, s93
	s_add_u32 s84, s30, 0x39040000
	s_addc_u32 s85, s31, 0
	s_lshl_b32 s86, s94, 4
	s_lshl_b32 s87, s95, 4
	v_mov_b32_e32 v1, 0
	s_mov_b64 s[4:5], 0x10000
	s_mov_b64 s[6:7], 0x20000
	s_mov_b64 s[8:9], 0x30000
	s_mov_b64 s[10:11], 0x6000
	s_mov_b64 s[12:13], 0x80
	s_mov_b64 s[14:15], 0x10080
	s_mov_b64 s[16:17], 0x2080
	s_mov_b64 s[18:19], 0x20080
	s_mov_b64 s[20:21], 0x4080
	s_mov_b64 s[36:37], 0x30080
	s_mov_b64 s[54:55], 0x6080
	s_mov_b32 s88, 0x3fffffc0
	s_movk_i32 s89, 0x84
	s_movk_i32 s90, 0x210
	s_mov_b64 s[56:57], 0x8000
	s_mov_b64 s[68:69], 0x18000
	s_mov_b64 s[70:71], 0x28000
	s_mov_b64 s[72:73], 0x38000
	s_mov_b32 s91, s94

; __device__ __forceinline__ ushort_t* wsb(const Params& p, size_t off) { return (ushort_t*)(p.ws + off); }
; __device__ __forceinline__ ushort_t* wts(const Params& p, size_t eoff) { return (ushort_t*)(p.ws + OFF_W) + eoff; }
; __device__ __forceinline__ int opaque_tid() { int t = threadIdx.x; asm volatile("" : "+v"(t)); return t; }
; template <bool MIX>
; __device__ __forceinline__ void phase_outproj_ln(const Params& p, int layer, const ushort_t* M, size_t w_out_off, char* smem) {
;   const float* xsrc = (layer == 0) ? p.in[I_X] : p.out;
;   float* out = p.out;
;   ushort_t* xb = wsb(p, OFF_XB);
;   const float* lg = p.in[I_LNG] + layer * 1024;
;   const float* lb = p.in[I_LNB] + layer * 1024;
;   float* Cs = (float*)smem;
;   float* sst = (float*)(smem + 73728);
;   for (int mt = blockIdx.x; mt < T_TOK / 128; mt += gridDim.x) {
;     const int tid = opaque_tid();
;     const int l32 = tid & 31, rgrp = tid >> 5;
;     const int row0 = mt * 128;
;     __syncthreads();
;     sst[tid] = 0.f;
;     f32x4 acc[8][4];
;     for (int nt = 0; nt < 8; ++nt) {
;       if ((nt & 1) == 0)
;         gemm_core256<false>(wts(p, w_out_off) + (long)(nt >> 1) * 256 * 1024, 1024, M + (long)row0 * 1024, 1024, 1024, smem, acc, 0, nullptr);
.Lprio7_skip:
	v_readlane_b32 s4, v225, 8
	v_readlane_b32 s5, v225, 9
	s_andn2_b64 vcc, exec, s[4:5]
	s_barrier
	v_cndmask_b32_e64 v0, 0, 1, s[4:5]
	v_cmp_ne_u32_e64 s[2:3], 1, v0
	s_nop 1
	v_writelane_b32 v225, s2, 10
	s_nop 1
	v_writelane_b32 v225, s3, 11
	s_cbranch_vccnz .LBB0_451
	s_add_u32 s8, s38, 0x1000
	s_addc_u32 s9, s39, 0
	s_add_u32 s10, s40, 0x1000
	s_addc_u32 s11, s41, 0
	s_add_u32 s2, s30, 0x39080000
	s_addc_u32 s3, s31, 0
	s_lshl_b32 s12, s96, 7
	s_lshl_b32 s4, s34, 7
	s_or_b32 s5, s12, 8
	s_add_u32 s14, s28, 8
	s_addc_u32 s15, s29, 0
	v_mov_b32_e32 v1, 0
	s_add_i32 s35, 0, 0x12040
	s_movk_i32 s37, 0xf800
	s_mov_b64 s[16:17], 0x20000
	s_mov_b64 s[18:19], 0x20040
	s_mov_b64 s[20:21], 0x1fc20100
	s_movk_i32 s55, 0x84
	s_mov_b32 s36, 0x3fd744fd
	s_mov_b64 s[44:45], 0x10000
	s_mov_b64 s[50:51], 0x200
	s_mov_b32 s84, 0x800000
	s_mov_b32 s85, s96
	s_mov_b32 s54, 0x3a800000
	s_mov_b64 s[56:57], 0x8000
	s_mov_b64 s[68:69], 0x100

; __device__ __forceinline__ ushort_t* wsb(const Params& p, size_t off) { return (ushort_t*)(p.ws + off); }
; __device__ __forceinline__ void phase_rwkv_mix(const Params& p) {
;   const float* x = p.out;
;   ushort_t* Ar = wsb(p, OFF_P + 4 * SLOT);
;   ushort_t* Ak = wsb(p, OFF_P + 5 * SLOT);
;   ushort_t* Av = wsb(p, OFF_P + 2 * SLOT);
;   ushort_t* Ag = wsb(p, OFF_P + 3 * SLOT);
;   const float* mu = p.in[I_RW_MU];
;   const long n4 = (long)T_TOK * 256;
;   for (long i = (long)blockIdx.x * 256 + threadIdx.x; i < n4; i += (long)gridDim.x * 256) {
;     const long tok = i >> 8;
;     const int c = (int)(i & 255) * 4;
;     const float4 xc = *(const float4*)(x + tok * 1024 + c);
;     float4 xp = make_float4(0.f, 0.f, 0.f, 0.f);
;     if ((tok & 4095) != 0) xp = *(const float4*)(x + (tok - 1) * 1024 + c);
;     const float dx = xp.x - xc.x, dy = xp.y - xc.y, dz = xp.z - xc.z, dw = xp.w - xc.w;
;     const float4 m0 = *(const float4*)(mu + 0 * 1024 + c), m2 = *(const float4*)(mu + 2 * 1024 + c);
;     const float4 m3 = *(const float4*)(mu + 3 * 1024 + c), m5 = *(const float4*)(mu + 5 * 1024 + c);
.LBB0_461:
	s_or_b64 exec, exec, s[6:7]
	s_cmp_lt_u32 s98, 0x100
	s_cbranch_scc1 .Lprio8_skip
	s_setprio 1
.Lprio8_skip:
	s_add_u32 s10, s30, 0x28000000
	s_mov_b32 s97, 0
	s_addc_u32 s11, s31, 0
	s_lshl_b64 s[0:1], s[96:97], 8
	v_lshl_add_u64 v[146:147], s[0:1], 0, v[140:141]
	s_mov_b64 s[0:1], 0x1000000
	v_cmp_gt_u64_e32 vcc, s[0:1], v[146:147]
	s_barrier
	s_and_saveexec_b64 s[6:7], vcc
	s_cbranch_execz .LBB0_466
	s_add_u32 s8, s74, 0x2000
	s_addc_u32 s9, s75, 0
	s_add_u32 s12, s74, 0x3000
	s_addc_u32 s13, s75, 0
	s_add_u32 s14, s74, 0x5000
	s_addc_u32 s15, s75, 0
	s_mov_b32 s35, s97
	s_lshl_b64 s[0:1], s[96:97], 10
	v_mov_b32_e32 v145, 0
	s_lshl_b64 s[16:17], s[34:35], 8
	v_lshl_add_u64 v[8:9], s[0:1], 0, v[144:145]
	s_lshl_b64 s[18:19], s[34:35], 10
	s_mov_b64 s[20:21], 0
	s_mov_b64 s[36:37], 0xffffff
	v_mov_b64_e32 v[10:11], v[146:147]
	s_cmp_eq_u32 s34, 0x200
	s_cbranch_scc0 .LBB0_464
	v_and_b32_e32 v32, 0x7f, v140
	v_lshrrev_b32_e32 v33, 7, v140
	s_lshl_b32 s16, s96, 7
	v_readfirstlane_b32 s0, v33
	v_lshlrev_b32_e32 v33, 4, v32
	v_lshlrev_b32_e32 v32, 5, v32
	s_lshl_b32 s0, s0, 6
	s_add_u32 s16, s16, s0
	s_lshl_b32 s17, s16, 12
	s_lshl_b32 s18, s16, 11
	s_and_b32 s19, s16, 0xfff
	v_add_u32_e32 v34, s17, v32
	v_add_u32_e32 v224, s18, v33
	v_add_u32_e32 v35, 0x1000, v34
	v_add_u32_e32 v36, 0x2000, v34
	v_add_u32_e32 v37, 0x3000, v34
	global_load_dwordx4 v[188:191], v32, s[74:75]
	global_load_dwordx4 v[192:195], v32, s[74:75] offset:16
	global_load_dwordx4 v[196:199], v32, s[8:9]
	global_load_dwordx4 v[200:203], v32, s[8:9] offset:16
	global_load_dwordx4 v[208:211], v32, s[12:13]
	global_load_dwordx4 v[212:215], v32, s[12:13] offset:16
	global_load_dwordx4 v[216:219], v32, s[14:15]
	global_load_dwordx4 v[220:223], v32, s[14:15] offset:16
	v_mov_b32_e32 v226, 0
	v_mov_b32_e32 v227, 0
	v_mov_b32_e32 v228, 0
	v_mov_b32_e32 v229, 0
	v_mov_b32_e32 v230, 0
	v_mov_b32_e32 v231, 0
	v_mov_b32_e32 v232, 0
	v_mov_b32_e32 v233, 0
	s_cmp_eq_u32 s19, 0
	s_cbranch_scc1 .Lmy_mix_go
	global_load_dwordx4 v[226:229], v34, s[28:29] offset:-4096
	global_load_dwordx4 v[230:233], v34, s[28:29] offset:-4080

; __device__ __forceinline__ ushort_t* wsb(const Params& p, size_t off) { return (ushort_t*)(p.ws + off); }
; __device__ __forceinline__ ushort_t* wts(const Params& p, size_t eoff) { return (ushort_t*)(p.ws + OFF_W) + eoff; }
; #define TILE_LOOP2(NTV) for (int q_ = blockIdx.x >> 3, mt = 0, nt = 0; tile_coords(q_, (NTV), mt, nt, 256); q_ += gridDim.x >> 3)
; __device__ __forceinline__ void phase_rwkv_inproj(const Params& p, int stage, char* smem) {
;   float* Cs = (float*)smem;
;   const ushort_t* xb = wsb(p, OFF_XB);
;   const ushort_t* A1 = wsb(p, OFF_P + (stage ? 2 : 4) * SLOT);
;   const ushort_t* A2 = wsb(p, OFF_P + (stage ? 3 : 5) * SLOT);
;   ushort_t* O1 = wsb(p, OFF_P + (stage ? 4 : 0) * SLOT);
;   ushort_t* O2 = wsb(p, OFF_P + (stage ? 5 : 1) * SLOT);
;   ushort_t* HID = wsb(p, OFF_HID);
;   const int NT = stage ? 17 : 16;
;   TILE_LOOP2(NT) {
;     int tid = threadIdx.x;
;     asm volatile("" : "+v"(tid));
;     const int row = tid >> 1, hf = tid & 1;
;     f32x4 acc[8][4];
;     if (nt < 16) {
;       gemm_core256<false>((nt < 8 ? A1 : A2) + (long)mt * 256 * 1024, 1024,
;                           wts(p, W_RWKV_IN1) + (long)(stage * 2048 + nt * 128) * 1024, 1024, 1024, smem, acc, 0, nullptr);
;     } else {
;       gemm_core256<true>(xb + (long)mt * 256 * 1024, 1024, wts(p, W_RWKV_IN) + (long)4096 * 2048, 2048, 2048, smem, acc, mt * 256, wsb(p, OFF_ZERO));
.LBB0_476:
	v_writelane_b32 v225, s34, 2
	s_nop 1
	v_writelane_b32 v225, s35, 3
	v_writelane_b32 v225, s96, 4
	s_nop 1
	v_writelane_b32 v225, s97, 5
	s_or_b64 exec, exec, s[6:7]
	s_cmp_lt_u32 s98, 0x100
	s_cbranch_scc1 .Lprio9_skip
	s_setprio 1
.Lprio9_skip:
	s_add_u32 s35, s30, 0x3bb40000
	s_addc_u32 s90, s31, 0
	s_add_u32 s8, s30, 0x3a280000
	s_addc_u32 s9, s31, 0
	s_add_u32 s12, s30, 0x3eb40000
	s_addc_u32 s13, s31, 0
	s_add_u32 s0, s30, 0x3af40000
	v_writelane_b32 v225, s0, 6
	s_addc_u32 s0, s31, 0
	s_mov_b32 s15, 0
	s_movk_i32 s54, 0xf800
	v_writelane_b32 v225, s0, 8
	v_mov_b32_e32 v1, 0
	s_mov_b64 s[44:45], 0x20040
	s_mov_b32 s0, 0x8000
	s_mov_b32 s1, 0x10000
	s_movk_i32 s4, 0xfc0
	s_mov_b32 s55, -1
	s_mov_b64 s[56:57], 0x1f800
	s_mov_b64 s[68:69], 0x3f800
	s_movk_i32 s5, 0xf80
	s_mov_b64 s[70:71], 0x5f800
	s_movk_i32 s84, 0xf40
	s_movk_i32 s85, 0xf800
	s_movk_i32 s91, 0x210
	s_mov_b32 s92, 0x3f200000
	s_mov_b32 s95, 0x3fb8aa3b
	s_mov_b32 s96, 0xc2ce8ed0
	s_mov_b32 s97, 0x42b17218
	v_mov_b32_e32 v141, 0x3ca908c9
	s_brev_b32 s20, -2
	s_mov_b32 s21, 0x18000
	s_mov_b32 s50, 0x20000
	s_mov_b32 s51, 0x28000
	s_mov_b32 s16, 0x30000
	v_mov_b32_e32 v143, 0x7f800000
	s_mov_b32 s18, 0
	s_mov_b32 s17, s94
	s_mov_b32 s72, s15
	s_barrier
	s_waitcnt vmcnt(0)
	s_branch .LBB0_479

; __device__ __forceinline__ ushort_t* wsb(const Params& p, size_t off) { return (ushort_t*)(p.ws + off); }
; __device__ __forceinline__ ushort_t* wts(const Params& p, size_t eoff) { return (ushort_t*)(p.ws + OFF_W) + eoff; }
; #define TILE_LOOP2(NTV) for (int q_ = blockIdx.x >> 3, mt = 0, nt = 0; tile_coords(q_, (NTV), mt, nt, 256); q_ += gridDim.x >> 3)
; __device__ __forceinline__ void phase_rwkv_inproj(const Params& p, int stage, char* smem) {
;   float* Cs = (float*)smem;
;   const ushort_t* xb = wsb(p, OFF_XB);
;   const ushort_t* A1 = wsb(p, OFF_P + (stage ? 2 : 4) * SLOT);
;   const ushort_t* A2 = wsb(p, OFF_P + (stage ? 3 : 5) * SLOT);
;   ushort_t* O1 = wsb(p, OFF_P + (stage ? 4 : 0) * SLOT);
;   ushort_t* O2 = wsb(p, OFF_P + (stage ? 5 : 1) * SLOT);
;   ushort_t* HID = wsb(p, OFF_HID);
;   const int NT = stage ? 17 : 16;
;   TILE_LOOP2(NT) {
;     int tid = threadIdx.x;
;     asm volatile("" : "+v"(tid));
;     const int row = tid >> 1, hf = tid & 1;
;     f32x4 acc[8][4];
;     if (nt < 16) {
;       gemm_core256<false>((nt < 8 ? A1 : A2) + (long)mt * 256 * 1024, 1024,
;                           wts(p, W_RWKV_IN1) + (long)(stage * 2048 + nt * 128) * 1024, 1024, 1024, smem, acc, 0, nullptr);
;     } else {
;       gemm_core256<true>(xb + (long)mt * 256 * 1024, 1024, wts(p, W_RWKV_IN) + (long)4096 * 2048, 2048, 2048, smem, acc, mt * 256, wsb(p, OFF_ZERO));
.Lprio10_skip:
	s_mov_b32 s15, 0
	s_movk_i32 s54, 0xf800
	v_mov_b32_e32 v1, 0
	s_mov_b64 s[44:45], 0x20040
	s_mov_b32 s4, 0x8000
	s_mov_b32 s5, 0x10000
	s_movk_i32 s84, 0xfc0
	s_mov_b32 s55, -1
	s_mov_b64 s[56:57], 0x1f800
	s_mov_b64 s[68:69], 0x3f800
	s_movk_i32 s85, 0xf80
	s_mov_b64 s[70:71], 0x5f800
	s_movk_i32 s0, 0xf40
	s_movk_i32 s1, 0xf800
	s_movk_i32 s95, 0x210
	s_mov_b32 s96, 0x3f200000
	s_mov_b32 s20, 0x3fb8aa3b
	s_mov_b32 s21, 0xc2ce8ed0
	s_mov_b32 s50, 0x42b17218
	v_mov_b32_e32 v141, 0x3ca908c9
	s_brev_b32 s51, -2
	s_mov_b32 s91, 0x18000
	s_mov_b32 s97, 0x20000
	s_mov_b32 s16, 0x28000
	s_mov_b32 s17, 0x30000
	v_mov_b32_e32 v143, 0x7f800000
	s_mov_b32 s18, 0
	s_mov_b32 s92, s94
	s_mov_b32 s72, s15
	s_barrier
	s_branch .LBB0_985

; __device__ __forceinline__ ushort_t* wsb(const Params& p, size_t off) { return (ushort_t*)(p.ws + off); }
; __device__ __forceinline__ ushort_t* wts(const Params& p, size_t eoff) { return (ushort_t*)(p.ws + OFF_W) + eoff; }
; #define TILE_LOOP(NTV) for (int q_ = blockIdx.x >> 3, mt = 0, nt = 0; tile_coords(q_, (NTV), mt, nt); q_ += gridDim.x >> 3)
; __device__ __forceinline__ void phase_rwkv_lorab(const Params& p, char* smem) {
;   float* Cs = (float*)smem;
;   const ushort_t* HID = wsb(p, OFF_HID);
;   ushort_t* EW = wsb(p, OFF_P + 2 * SLOT);
;   ushort_t* AA = wsb(p, OFF_P + 3 * SLOT);
;   const float* w0 = p.in[I_RW_W0];
;   const float* a0 = p.in[I_RW_A0];
;   TILE_LOOP(16) {
;     int tid = threadIdx.x;
;     asm volatile("" : "+v"(tid));
;     const int row = tid >> 1, hf = tid & 1;
;     const int which = nt >> 3, row0 = mt * 128;
;     nt &= 7;
;     f32x4 acc[4][4];
;     gemm_core<false, false>(HID + (long)row0 * 128 + which * 64, 128, wts(p, which ? W_RWKV_ALB : W_RWKV_WLB) + (long)nt * 128 * 64, 64, 64, smem, acc);
.Lprio11_skip:
	s_cmpk_gt_u32 s74, 0x1fff
	s_barrier
	s_cbranch_scc1 .LBB0_1498
	s_lshr_b32 s0, s74, 6
	s_and_b32 s0, s0, 0x78
	s_or_b32 s20, s0, s93
	s_lshl_b32 s0, s94, 4
	s_lshl_b32 s1, s92, 4
	s_mov_b32 s2, 0x2300000
	s_movk_i32 s3, 0x70
	s_movk_i32 s4, 0x780
	v_mov_b32_e32 v5, 0
	s_mov_b64 s[6:7], 0x2000
	s_mov_b64 s[8:9], 0x1000
	s_mov_b64 s[12:13], 0x4000
	s_mov_b64 s[14:15], 0x6000
	s_mov_b64 s[16:17], 0x3000
	s_mov_b32 s5, 0x3fffffc0
	s_movk_i32 s19, 0x84
	s_movk_i32 s44, 0x210
	s_mov_b32 s45, 0x8000
	s_mov_b32 s50, 0x10000
	s_mov_b32 s51, 0x18000
	s_mov_b32 s54, 0x20000
	s_mov_b32 s55, 0x28000
	s_mov_b32 s56, 0x30000
	s_mov_b32 s18, 0x3f1b4598
	s_mov_b32 s57, s94
	s_branch .LBB0_1494

; __device__ __forceinline__ ushort_t* wsb(const Params& p, size_t off) { return (ushort_t*)(p.ws + off); }
; __device__ __forceinline__ int opaque_tid() { int t = threadIdx.x; asm volatile("" : "+v"(t)); return t; }
; __device__ __forceinline__ void phase_rwkv_scan(const Params& p, char* smem) {
;   const ushort_t* R = wsb(p, OFF_P + 0 * SLOT);
;   ushort_t* M = wsb(p, OFF_XB);
;   const ushort_t* Kb = wsb(p, OFF_P + 1 * SLOT);
;   const ushort_t* Vb = wsb(p, OFF_P + 4 * SLOT);
;   const ushort_t* G = wsb(p, OFF_P + 5 * SLOT);
;   const ushort_t* EW = wsb(p, OFF_P + 2 * SLOT);
;   const ushort_t* AA = wsb(p, OFF_P + 3 * SLOT);
;   constexpr int ARR = RW_TC * 64;
;   constexpr int SETF = 7 * ARR + 64;
;   float* sbase = (float*)smem;
;   const int tid = opaque_tid(), lane = tid & 63, wave = tid >> 6;
;   const int vp = tid >> 3, kq = tid & 7;
;   for (int item = blockIdx.x; item < 256; item += gridDim.x) {
;     const int b = item >> 4, h = item & 15;
;     const int col = h * 64 + lane;
;     const float kkc = p.in[I_RW_KK][col], kac = p.in[I_RW_KA][col], rkc = p.in[I_RW_RK][col];
;     const float gng = p.in[I_RW_GNG][col], gnb = p.in[I_RW_GNB][col];
;     const long gbase = (long)b * 4096 * 1024 + col;
;     float S[16];
; #pragma unroll
;     for (int j = 0; j < 16; ++j) S[j] = 0.f;
.Lprio12_skip:
	s_barrier
	s_cmpk_gt_i32 s74, 0xff
	s_cbranch_scc1 .LBB0_1550
	v_and_b32_e32 v68, 7, v140
	v_lshrrev_b32_e32 v69, 3, v140
	v_lshrrev_b32_e32 v70, 4, v140
	v_and_b32_e32 v71, 15, v140
	v_lshlrev_b32_e32 v141, 2, v69
	v_lshlrev_b32_e32 v76, 8, v70
	v_lshlrev_b32_e32 v77, 4, v71
	v_add_u32_e32 v143, v76, v77
	v_lshlrev_b32_e32 v144, 2, v70
	s_mov_b32 s12, 0xffff0000
	s_mov_b32 s8, 0xbfb8aa3b
	s_mov_b32 s14, 0xbc800000
	s_mov_b32 s0, s74

; __device__ __forceinline__ ushort_t* wsb(const Params& p, size_t off) { return (ushort_t*)(p.ws + off); }
; __device__ __forceinline__ ushort_t* wts(const Params& p, size_t eoff) { return (ushort_t*)(p.ws + OFF_W) + eoff; }
; __device__ __forceinline__ int opaque_tid() { int t = threadIdx.x; asm volatile("" : "+v"(t)); return t; }
; template <bool MIX>
; __device__ __forceinline__ void phase_outproj_ln(const Params& p, int layer, const ushort_t* M, size_t w_out_off, char* smem) {
;   const float* xsrc = (layer == 0) ? p.in[I_X] : p.out;
;   float* out = p.out;
;   ushort_t* xb = wsb(p, OFF_XB);
;   const float* lg = p.in[I_LNG] + layer * 1024;
;   const float* lb = p.in[I_LNB] + layer * 1024;
;   float* Cs = (float*)smem;
;   float* sst = (float*)(smem + 73728);
;   for (int mt = blockIdx.x; mt < T_TOK / 128; mt += gridDim.x) {
;     const int tid = opaque_tid();
;     const int l32 = tid & 31, rgrp = tid >> 5;
;     const int row0 = mt * 128;
;     __syncthreads();
;     sst[tid] = 0.f;
;     f32x4 acc[8][4];
;     for (int nt = 0; nt < 8; ++nt) {
;       if ((nt & 1) == 0)
;         gemm_core256<false>(wts(p, w_out_off) + (long)(nt >> 1) * 256 * 1024, 1024, M + (long)row0 * 1024, 1024, 1024, smem, acc, 0, nullptr);
.Lprio13_skip:
	v_readlane_b32 s0, v225, 10
	v_readlane_b32 s1, v225, 11
	s_and_b64 vcc, exec, s[0:1]
	s_barrier
	s_cbranch_vccnz .LBB0_1598
	s_add_u32 s8, s38, 0x2000
	s_addc_u32 s9, s39, 0
	s_add_u32 s12, s40, 0x2000
	s_addc_u32 s13, s41, 0
	s_add_u32 s0, s30, 0x3a340000
	s_addc_u32 s1, s31, 0
	s_lshl_b32 s14, s74, 7
	s_lshl_b32 s2, s96, 7
	s_or_b32 s3, s14, 8
	s_add_u32 s16, s28, 8
	s_addc_u32 s17, s29, 0
	v_mov_b32_e32 v1, 0
	s_add_i32 s4, 0, 0x12040
	s_movk_i32 s5, 0xf800
	s_mov_b64 s[18:19], 0x20000
	s_mov_b64 s[20:21], 0x20040
	s_mov_b64 s[36:37], 0x3a3a00c0
	s_mov_b64 s[44:45], 0x300000c0
	s_mov_b64 s[50:51], 0x300200c0
	s_mov_b64 s[52:53], 0x3a340100
	s_mov_b64 s[54:55], 0x3a360100
	s_mov_b64 s[56:57], 0x3a380100
	s_mov_b64 s[58:59], 0x3a3a0100
	s_mov_b64 s[60:61], 0x30000100
	s_mov_b64 s[62:63], 0x30020100
	s_movk_i32 s35, 0x84
	s_mov_b32 s64, 0x3fd744fd
	s_mov_b64 s[66:67], 0x10000
	s_mov_b64 s[68:69], 0x200
	s_mov_b32 s65, 0x800000
	s_mov_b32 s71, s74
	s_mov_b32 s70, 0x3a800000
	s_mov_b64 s[72:73], 0x8000
	s_mov_b64 s[74:75], 0x100

; __device__ __forceinline__ ushort_t* wsb(const Params& p, size_t off) { return (ushort_t*)(p.ws + off); }
; __device__ __forceinline__ ushort_t* wts(const Params& p, size_t eoff) { return (ushort_t*)(p.ws + OFF_W) + eoff; }
; __device__ __forceinline__ void phase_ret_inproj(const Params& p, char* smem) {
;   const int tid = opaque_tid(), row = tid >> 1, hf = tid & 1;
;   float* Cs = (float*)smem;
;   const ushort_t* xb = wsb(p, OFF_XB);
;   ushort_t* QR = wsb(p, OFF_P + 0 * SLOT);
;   ushort_t* KR = wsb(p, OFF_P + 1 * SLOT);
;   ushort_t* KT = wsb(p, OFF_P + 2 * SLOT);
;   ushort_t* VT = wsb(p, OFF_P + 3 * SLOT);
;   ushort_t* G = wsb(p, OFF_P + 4 * SLOT);
;   const int NT = 32;
;   TILE_LOOP(NT) {
;     const int row0 = mt * 128;
;     f32x4 acc[4][4];
;     gemm_core<false, false>(xb + (long)row0 * 1024, 1024, wts(p, W_RET_IN) + (long)nt * 128 * 1024, 1024, 1024, smem, acc);
;     if (nt >= 16 && nt < 24) stage_acc_T(Cs, acc); else stage_acc(Cs, acc);
;     __syncthreads();
;     const long tok = row0 + row;
;     const int b = row0 >> 12, s0 = row0 & 4095;
;     if (nt < 16) {
;       const bool isk = nt >= 8;
;       const int hh = (nt & 7) >> 1, pp = nt & 1;
;       const float pos = (float)(s0 + row);
;       float* cr = Cs + row * CS_LD;
;       const float ksc = isk ? 0.0625f : 1.f;
; #pragma unroll 4
;       for (int e = 0; e < 32; ++e) {
;         const int c = hf * 32 + e;
;         const int i = pp * 64 + c;
;         const float inv = __builtin_amdgcn_exp2f(-(float)i * (13.287712379549449f / 128.f));
;         float sn, cs_;
;         __sincosf(pos * inv, &sn, &cs_);
;         const float x1 = cr[c], x2 = cr[c + 64];
;         cr[c] = (x1 * cs_ - x2 * sn) * ksc;
;         cr[c + 64] = (x2 * cs_ + x1 * sn) * ksc;
;       }
;       __syncthreads();
;       store_tile_cm((isk ? KR : QR) + (long)row0 * 1024 + hh * 256, 1024, Cs, [](float v) { return v; },
;                     [&](int c) { return pp * 64 + c + (c >= 64 ? 64 : 0); });
;       if (isk) {
;         const int feat = row, th = hf;
;         const int dim = (feat < 64) ? pp * 64 + feat : 128 + pp * 64 + (feat - 64);
;         const float l2g = ret_log2g(hh);
;         store_col64(KT + ((long)((b * 4 + hh) * 256 + dim)) * 4096 + s0 + th * 64, Cs, feat, th,
;                     [&](float v, int tl) { return v * __builtin_amdgcn_exp2f((float)(127 - ((s0 + tl) & 127)) * l2g); });
.Lprio14_skip:
	v_mov_b32_e32 v0, v140
	s_cmpk_gt_u32 s74, 0x3fff
	s_barrier
	s_cbranch_scc1 .LBB0_1631
	s_lshr_b32 s0, s74, 6
	s_and_b32 s0, s0, 0xf8
	v_ashrrev_i32_e32 v68, 1, v0
	s_or_b32 s2, s0, s93
	s_movk_i32 s0, 0x210
	v_and_b32_e32 v1, 1, v0
	v_mul_lo_u32 v2, v68, s0
	s_movk_i32 s1, 0xfdf4
	v_add_u32_e32 v3, 0, v2
	v_lshlrev_b32_e32 v0, 6, v1
	v_mul_lo_u32 v5, v68, s1
	v_mul_u32_u24_e32 v6, 0x8400, v1
	v_add3_u32 v70, v3, v5, v6
	v_xor_b32_e32 v3, 0x7f, v0
	v_cvt_f32_ubyte0_e32 v71, v3
	v_xor_b32_e32 v3, 0x7e, v0
	v_cvt_f32_ubyte0_e32 v72, v3
	v_xor_b32_e32 v3, 0x7d, v0
	v_cvt_f32_ubyte0_e32 v73, v3
	v_xor_b32_e32 v3, 0x7c, v0
	v_cvt_f32_ubyte0_e32 v74, v3
	v_xor_b32_e32 v3, 0x7b, v0
	v_cvt_f32_ubyte0_e32 v75, v3
	v_xor_b32_e32 v3, 0x7a, v0
	v_cvt_f32_ubyte0_e32 v76, v3
	v_xor_b32_e32 v3, 0x79, v0
	v_cvt_f32_ubyte0_e32 v77, v3
	v_xor_b32_e32 v3, 0x78, v0
	v_cvt_f32_ubyte0_e32 v78, v3
	v_xor_b32_e32 v3, 0x77, v0
	v_cvt_f32_ubyte0_e32 v79, v3
	v_xor_b32_e32 v3, 0x76, v0
	s_waitcnt vmcnt(19)
	v_cvt_f32_ubyte0_e32 v80, v3
	v_xor_b32_e32 v3, 0x75, v0
	s_waitcnt vmcnt(18)
	v_cvt_f32_ubyte0_e32 v81, v3
	v_xor_b32_e32 v3, 0x74, v0
	s_waitcnt vmcnt(17)
	v_cvt_f32_ubyte0_e32 v82, v3
	v_xor_b32_e32 v3, 0x73, v0
	s_waitcnt vmcnt(16)
	v_cvt_f32_ubyte0_e32 v83, v3
	v_xor_b32_e32 v3, 0x72, v0
	s_waitcnt vmcnt(15)
	v_cvt_f32_ubyte0_e32 v84, v3
	v_xor_b32_e32 v3, 0x71, v0
	s_waitcnt vmcnt(14)
	v_cvt_f32_ubyte0_e32 v85, v3
	v_xor_b32_e32 v3, 0x70, v0
	s_waitcnt vmcnt(13)
	v_cvt_f32_ubyte0_e32 v86, v3
	v_xor_b32_e32 v3, 0x6f, v0
	s_waitcnt vmcnt(12)
	v_cvt_f32_ubyte0_e32 v87, v3
	v_xor_b32_e32 v3, 0x6e, v0
	s_waitcnt vmcnt(11)
	v_cvt_f32_ubyte0_e32 v88, v3
	v_xor_b32_e32 v3, 0x6d, v0
	s_waitcnt vmcnt(10)
	v_cvt_f32_ubyte0_e32 v89, v3
	v_xor_b32_e32 v3, 0x6c, v0
	s_waitcnt vmcnt(3)
	v_cvt_f32_ubyte0_e32 v90, v3
	v_xor_b32_e32 v3, 0x6b, v0
	v_cvt_f32_ubyte0_e32 v91, v3
	v_xor_b32_e32 v3, 0x6a, v0
	s_waitcnt vmcnt(2)
	v_cvt_f32_ubyte0_e32 v92, v3
	v_xor_b32_e32 v3, 0x69, v0
	v_cvt_f32_ubyte0_e32 v93, v3
	v_xor_b32_e32 v3, 0x68, v0
	s_waitcnt vmcnt(1)
	v_cvt_f32_ubyte0_e32 v94, v3
	v_xor_b32_e32 v3, 0x67, v0
	v_cvt_f32_ubyte0_e32 v95, v3
	v_xor_b32_e32 v3, 0x66, v0
	v_cvt_f32_ubyte0_e32 v96, v3
	v_xor_b32_e32 v3, 0x65, v0
	s_waitcnt vmcnt(0)
	v_cvt_f32_ubyte0_e32 v97, v3
	v_xor_b32_e32 v3, 0x64, v0
	v_cvt_f32_ubyte0_e32 v98, v3
	v_xor_b32_e32 v3, 0x63, v0
	v_cvt_f32_ubyte0_e32 v99, v3
	v_xor_b32_e32 v3, 0x62, v0
	v_cvt_f32_ubyte0_e32 v100, v3
	v_xor_b32_e32 v3, 0x61, v0
	v_cvt_f32_ubyte0_e32 v101, v3
	v_xor_b32_e32 v3, 0x60, v0
	v_cvt_f32_ubyte0_e32 v102, v3
	v_xor_b32_e32 v3, 0x5f, v0
	v_cvt_f32_ubyte0_e32 v103, v3
	v_xor_b32_e32 v3, 0x5e, v0
	v_cvt_f32_ubyte0_e32 v104, v3
	v_xor_b32_e32 v3, 0x5d, v0
	v_cvt_f32_ubyte0_e32 v105, v3
	v_xor_b32_e32 v3, 0x5c, v0
	v_cvt_f32_ubyte0_e32 v106, v3
	v_xor_b32_e32 v3, 0x5b, v0
	v_cvt_f32_ubyte0_e32 v107, v3
	v_xor_b32_e32 v3, 0x5a, v0
	v_cvt_f32_ubyte0_e32 v108, v3
	v_xor_b32_e32 v3, 0x59, v0
	v_cvt_f32_ubyte0_e32 v109, v3
	v_xor_b32_e32 v3, 0x58, v0
	v_cvt_f32_ubyte0_e32 v110, v3
	v_xor_b32_e32 v3, 0x57, v0
	v_cvt_f32_ubyte0_e32 v111, v3
	v_xor_b32_e32 v3, 0x56, v0
	v_cvt_f32_ubyte0_e32 v112, v3
	v_xor_b32_e32 v3, 0x55, v0
	v_cvt_f32_ubyte0_e32 v113, v3
	v_xor_b32_e32 v3, 0x54, v0
	v_cvt_f32_ubyte0_e32 v114, v3
	v_xor_b32_e32 v3, 0x53, v0
	v_cvt_f32_ubyte0_e32 v115, v3
	v_xor_b32_e32 v3, 0x52, v0
	v_cvt_f32_ubyte0_e32 v116, v3
	v_xor_b32_e32 v3, 0x51, v0
	v_cvt_f32_ubyte0_e32 v117, v3
	v_xor_b32_e32 v3, 0x50, v0
	v_cvt_f32_ubyte0_e32 v118, v3
	v_xor_b32_e32 v3, 0x4f, v0
	v_cvt_f32_ubyte0_e32 v119, v3
	v_xor_b32_e32 v3, 0x4e, v0
	v_cvt_f32_ubyte0_e32 v120, v3
	v_xor_b32_e32 v3, 0x4d, v0
	v_cvt_f32_ubyte0_e32 v121, v3
	v_xor_b32_e32 v3, 0x4c, v0
	v_cvt_f32_ubyte0_e32 v122, v3
	v_xor_b32_e32 v3, 0x4b, v0
	v_cvt_f32_ubyte0_e32 v123, v3
	v_xor_b32_e32 v3, 0x4a, v0
	v_cvt_f32_ubyte0_e32 v124, v3
	v_xor_b32_e32 v3, 0x49, v0
	v_cvt_f32_ubyte0_e32 v125, v3
	v_xor_b32_e32 v3, 0x48, v0
	v_cvt_f32_ubyte0_e32 v126, v3
	v_xor_b32_e32 v3, 0x47, v0
	v_cvt_f32_ubyte0_e32 v127, v3
	v_xor_b32_e32 v3, 0x46, v0
	v_cvt_f32_ubyte0_e32 v128, v3
	v_xor_b32_e32 v3, 0x45, v0
	v_cvt_f32_ubyte0_e32 v129, v3
	v_xor_b32_e32 v3, 0x44, v0
	v_cvt_f32_ubyte0_e32 v130, v3
	v_xor_b32_e32 v3, 0x43, v0
	v_cvt_f32_ubyte0_e32 v131, v3
	v_xor_b32_e32 v3, 0x42, v0
	v_cvt_f32_ubyte0_e32 v132, v3
	v_xor_b32_e32 v3, 0x41, v0
	v_lshlrev_b32_e32 v69, 5, v1
	v_add_u32_e32 v4, 64, v68
	v_cvt_f32_ubyte0_e32 v133, v3
	v_xor_b32_e32 v3, 64, v0
	v_cmp_gt_i32_e32 vcc, 64, v68
	s_add_u32 s4, s30, 0x3a540000
	v_lshlrev_b32_e32 v1, 7, v1
	s_mov_b32 s9, 0
	v_mov_b32_e32 v65, 0
	s_movk_i32 s1, 0x70
	v_cvt_f32_ubyte0_e32 v134, v3
	v_cndmask_b32_e32 v135, v4, v68, vcc
	s_addc_u32 s5, s31, 0
	s_lshl_b32 s35, s94, 4
	s_lshl_b32 s74, s92, 4
	s_lshl_b32 s75, s94, 6
	s_lshl_b32 s76, s92, 6
	v_add3_u32 v136, v2, v1, 0
	s_mov_b64 s[12:13], 0x10000
	s_mov_b64 s[14:15], 0x20000
	s_mov_b64 s[16:17], 0x30000
	s_mov_b32 s77, 0x8000
	s_mov_b64 s[18:19], 0x30000100
	s_mov_b64 s[20:21], 0x3a540100
	s_mov_b64 s[36:37], 0x30010100
	s_mov_b64 s[44:45], 0x3a550100
	s_mov_b64 s[50:51], 0x30020100
	s_mov_b64 s[52:53], 0x3a560100
	s_mov_b64 s[54:55], 0x30030100
	s_mov_b64 s[56:57], 0x3a570100
	s_mov_b32 s78, 0x3fffffc0
	s_movk_i32 s79, 0x84
	s_mov_b32 s80, 0x10000
	s_mov_b32 s81, 0x18000
	s_mov_b32 s82, 0x20000
	s_mov_b32 s83, 0x28000
	s_mov_b32 s84, 0x30000
	s_mov_b32 s85, 0x40000
	s_mov_b32 s86, 0x60000
	s_mov_b32 s87, 0x80000
	s_mov_b32 s88, 0xa0000
	s_mov_b32 s89, 0xc0000
	s_mov_b32 s90, 0x800000
	v_lshlrev_b32_e32 v66, 1, v0
	v_mov_b32_e32 v137, 0x3d800000
	v_mov_b32_e32 v138, 0x42000000
	s_mov_b32 s91, s94
	s_branch .LBB0_1611

; __device__ __forceinline__ ushort_t* wsb(const Params& p, size_t off) { return (ushort_t*)(p.ws + off); }
; __device__ __forceinline__ int opaque_tid() { int t = threadIdx.x; asm volatile("" : "+v"(t)); return t; }
; __device__ __forceinline__ void phase_ret_passA(const Params& p, char* smem) {
;   const int tid = opaque_tid(), row = tid >> 1, hf = tid & 1;
;   float* Cs = (float*)smem;
;   const ushort_t* KT = wsb(p, OFF_P + 2 * SLOT);
;   const ushort_t* VT = wsb(p, OFF_P + 3 * SLOT);
;   ushort_t* ST = wsb(p, OFF_P + 5 * SLOT);
;   for (int t = blockIdx.x; t < 64 * 31 * 4; t += gridDim.x) {
;     const int q4 = t & 3, dh = q4 >> 1, eh = q4 & 1, c = (t >> 2) % 31, bh = (t >> 2) / 31;
;     f32x4 acc[4][4];
;     gemm_core<false, false>(KT + ((long)(bh * 256 + dh * 128)) * 4096 + c * 128, 4096,
;                             VT + ((long)(bh * 256 + eh * 128)) * 4096 + c * 128, 4096, 128, smem, acc);
.Lprio15_skip:
	v_mov_b32_e32 v0, v140
	s_cmpk_gt_i32 s74, 0x1eff
	s_barrier
	s_cbranch_scc1 .LBB0_1644
	s_lshl_b32 s0, s74, 7
	s_lshl_b32 s1, s96, 7
	s_lshl_b32 s2, s74, 6
	s_lshl_b32 s3, s96, 6
	s_movk_i32 s4, 0x70
	s_movk_i32 s5, 0x780
	v_mov_b32_e32 v9, 0
	s_movk_i32 s34, 0x4000
	s_mov_b64 s[6:7], 0x40000
	s_mov_b64 s[8:9], 0x80000
	s_movk_i32 s35, 0x2000
	s_movk_i32 s44, 0x6000
	s_mov_b64 s[12:13], 0xc0000
	s_mov_b32 s45, 0x8000
	s_mov_b32 s48, 0xc000
	s_mov_b64 s[14:15], 0x80
	s_mov_b64 s[16:17], 0x40080
	s_mov_b64 s[18:19], 0x80080
	s_mov_b32 s49, 0xa000
	s_mov_b64 s[20:21], 0xc0080
	s_movk_i32 s50, 0x210
	s_mov_b32 s51, s74
	s_waitcnt vmcnt(0)

; __device__ __forceinline__ ushort_t* wsb(const Params& p, size_t off) { return (ushort_t*)(p.ws + off); }
; __device__ __forceinline__ float ret_log2g(int h) { return log2f(1.f - __builtin_amdgcn_exp2f(-5.f - (float)h)); }
; __device__ __forceinline__ void phase_ret_passB(const Params& p) {
;   ushort_t* ST = wsb(p, OFF_P + 5 * SLOT);
;   const long nwork = (long)64 * 256 * 32;
;   for (long w = (long)blockIdx.x * 256 + threadIdx.x; w < nwork; w += (long)gridDim.x * 256) {
;     const int bh = (int)(w >> 13), rem = (int)(w & 8191);
;     const float gC = __builtin_amdgcn_exp2f(128.f * ret_log2g(bh & 3));
;     float run[8];
; #pragma unroll
;     for (int e = 0; e < 8; ++e) run[e] = 0.f;
;     ushort_t* base = ST + (long)bh * 32 * 65536 + (long)rem * 8;
.Lprio16_skip:
	s_mov_b64 s[0:1], 0x80000
	v_cmp_gt_u64_e32 vcc, s[0:1], v[146:147]
	s_barrier
	s_and_saveexec_b64 s[6:7], vcc
	s_cbranch_execz .LBB0_1661
	s_mov_b32 s97, 0
	s_lshl_b64 s[0:1], s[74:75], 11
	v_mov_b32_e32 v143, 0
	s_lshl_b64 s[8:9], s[96:97], 8
	v_lshl_add_u64 v[0:1], s[0:1], 0, v[142:143]
	s_lshl_b64 s[12:13], s[96:97], 11
	s_mov_b64 s[14:15], 0
	s_mov_b32 s0, 0x1fff0
	s_mov_b32 s1, 0x800000
	v_mov_b32_e32 v26, 0x42000000
	s_mov_b64 s[16:17], 0x7ffff
	s_branch .LBB0_1657

; __device__ __forceinline__ ushort_t* wsb(const Params& p, size_t off) { return (ushort_t*)(p.ws + off); }
; __device__ __forceinline__ float ret_log2g(int h) { return log2f(1.f - __builtin_amdgcn_exp2f(-5.f - (float)h)); }
; __device__ __forceinline__ void phase_ret_passC(const Params& p, char* smem) {
;   float* Cs = (float*)smem;
;   const ushort_t* QR = wsb(p, OFF_P + 0 * SLOT);
;   const ushort_t* KR = wsb(p, OFF_P + 1 * SLOT);
;   ushort_t* M = wsb(p, OFF_P + 1 * SLOT);
;   const ushort_t* VT = wsb(p, OFF_P + 3 * SLOT);
;   const ushort_t* G = wsb(p, OFF_P + 4 * SLOT);
;   const ushort_t* ST = wsb(p, OFF_P + 5 * SLOT);
;   ushort_t* scr = wsb(p, OFF_SCR) + (long)blockIdx.x * 16384;
;   const float* gng = p.in[I_RET_GNG];
;   for (int t = blockIdx.x; t < 64 * 32; t += gridDim.x) {
;     int tid = threadIdx.x;
;     asm volatile("" : "+v"(tid));
;     const int lane = tid & 63, wave = tid >> 6, wp = wave >> 1, g = lane >> 4, row = tid >> 1, hf = tid & 1;
;     const int c = t & 31, bh = t >> 5, b = bh >> 2, hh = bh & 3;
;     const long tok0 = (long)b * 4096 + c * 128;
;     const float l2g = ret_log2g(hh);
;     f32x4 acc[4][4];
;     gemm_core<false, false>(QR + tok0 * 1024 + hh * 256, 1024, KR + tok0 * 1024 + hh * 256, 1024, 256, smem, acc);
.Lprio17_skip:
	s_cmpk_gt_i32 s74, 0x7ff
	s_barrier
	s_cbranch_scc1 .LBB0_1695
	s_lshl_b64 s[0:1], s[74:75], 15
	s_add_u32 s0, s30, s0
	s_addc_u32 s1, s31, s1
	s_add_u32 s12, s0, 0x3cb40000
	s_mov_b32 s0, s74
	s_addc_u32 s13, s1, 0
	s_mov_b32 s15, 0
	s_movk_i32 s3, 0x70
	s_movk_i32 s35, 0x780
	v_mov_b32_e32 v65, 0
	s_mov_b64 s[16:17], 0x10000
	s_mov_b64 s[18:19], 0x20000
	s_mov_b64 s[20:21], 0x30000
	s_mov_b64 s[36:37], 0x80
	s_mov_b64 s[44:45], 0x10080
	s_mov_b64 s[46:47], 0x20080
	s_mov_b64 s[48:49], 0x30080
	s_mov_b64 s[50:51], 0x100
	s_mov_b64 s[52:53], 0x10100
	s_mov_b64 s[54:55], 0x20100
	s_mov_b64 s[56:57], 0x30100
	s_mov_b64 s[58:59], 0x180
	s_mov_b64 s[60:61], 0x10180
	s_mov_b64 s[62:63], 0x20180
	s_mov_b64 s[64:65], 0x30180
	s_mov_b32 s87, 0x800000
	v_mov_b32_e32 v108, 0x42000000
	s_mov_b32 s89, 0x3fffffc0
	s_movk_i32 s92, 0x84
	s_movk_i32 s93, 0x210
	s_mov_b32 s94, 0x5040100
	s_mov_b64 s[66:67], 0x4000
	s_mov_b64 s[68:69], 0x4080
	s_mov_b64 s[70:71], 0x6000
	s_mov_b64 s[72:73], 0xc0000
	s_mov_b64 s[74:75], 0x2080
	s_mov_b64 s[76:77], 0x40080
	s_mov_b64 s[78:79], 0x80080
	s_mov_b64 s[80:81], 0x6080
	s_mov_b64 s[82:83], 0xc0080
	s_mov_b32 s86, 0x3b800000
	s_mov_b32 s88, 0x358637bd
	s_mov_b32 s95, s0

; __device__ __forceinline__ ushort_t* wsb(const Params& p, size_t off) { return (ushort_t*)(p.ws + off); }
; __device__ __forceinline__ ushort_t* wts(const Params& p, size_t eoff) { return (ushort_t*)(p.ws + OFF_W) + eoff; }
; __device__ __forceinline__ int opaque_tid() { int t = threadIdx.x; asm volatile("" : "+v"(t)); return t; }
; template <bool MIX>
; __device__ __forceinline__ void phase_outproj_ln(const Params& p, int layer, const ushort_t* M, size_t w_out_off, char* smem) {
;   const float* xsrc = (layer == 0) ? p.in[I_X] : p.out;
;   float* out = p.out;
;   ushort_t* xb = wsb(p, OFF_XB);
;   const float* lg = p.in[I_LNG] + layer * 1024;
;   const float* lb = p.in[I_LNB] + layer * 1024;
;   float* Cs = (float*)smem;
;   float* sst = (float*)(smem + 73728);
;   for (int mt = blockIdx.x; mt < T_TOK / 128; mt += gridDim.x) {
;     const int tid = opaque_tid();
;     const int l32 = tid & 31, rgrp = tid >> 5;
;     const int row0 = mt * 128;
;     __syncthreads();
;     sst[tid] = 0.f;
;     f32x4 acc[8][4];
;     for (int nt = 0; nt < 8; ++nt) {
;       if ((nt & 1) == 0)
;         gemm_core256<false>(wts(p, w_out_off) + (long)(nt >> 1) * 256 * 1024, 1024, M + (long)row0 * 1024, 1024, 1024, smem, acc, 0, nullptr);
.Lprio18_skip:
	v_readlane_b32 s0, v225, 10
	v_readlane_b32 s1, v225, 11
	s_and_b64 vcc, exec, s[0:1]
	s_barrier
	s_cbranch_vccnz .LBB0_1754
	s_add_u32 s4, s38, 0x3000
	s_addc_u32 s5, s39, 0
	s_add_u32 s6, s40, 0x3000
	s_addc_u32 s7, s41, 0
	s_add_u32 s3, s30, 0x3ad40000
	s_addc_u32 s34, s31, 0
	s_lshl_b32 s8, s74, 7
	s_mov_b32 s0, s96
	v_writelane_b32 v225, s0, 2
	s_lshl_b32 s35, s96, 7
	s_or_b32 s79, s8, 8
	v_writelane_b32 v225, s1, 3
	s_add_u32 s0, s28, 8
	s_addc_u32 s1, s29, 0
	v_writelane_b32 v225, s0, 16
	v_mov_b32_e32 v1, 0
	s_mov_b32 s2, s74
	v_writelane_b32 v225, s1, 17
	s_add_u32 s0, s28, 0x200
	s_addc_u32 s1, s29, 0
	s_add_u32 s14, s28, 0x400
	s_addc_u32 s15, s29, 0
	s_add_u32 s16, s28, 0x600
	s_addc_u32 s17, s29, 0
	s_add_u32 s18, s28, 0x800
	s_addc_u32 s19, s29, 0
	s_add_u32 s20, s28, 0xa00
	s_addc_u32 s21, s29, 0
	s_add_u32 s24, s28, 0xc00
	s_addc_u32 s25, s29, 0
	s_add_u32 s26, s28, 0xe00
	v_writelane_b32 v225, s0, 18
	s_addc_u32 s27, s29, 0
	s_add_i32 s13, 0, 0x12040
	s_movk_i32 s96, 0xf800
	s_mov_b64 s[36:37], 0x20000
	s_mov_b64 s[38:39], 0x20040
	s_mov_b64 s[40:41], 0x60040
	s_mov_b64 s[42:43], 0x3ad40080
	s_mov_b64 s[44:45], 0x3ad60080
	s_mov_b64 s[46:47], 0x3ad80080
	s_mov_b64 s[48:49], 0x3ada0080
	s_mov_b64 s[50:51], 0x8000080
	s_mov_b64 s[52:53], 0x8020080
	s_mov_b64 s[54:55], 0x3ad400c0
	s_mov_b64 s[56:57], 0x3ad600c0
	s_mov_b64 s[58:59], 0x3ad800c0
	s_mov_b64 s[60:61], 0x3ada00c0
	s_mov_b64 s[62:63], 0x80000c0
	s_mov_b64 s[64:65], 0x80200c0
	s_mov_b64 s[66:67], 0x3ad40100
	s_mov_b64 s[68:69], 0x3ad60100
	s_mov_b64 s[70:71], 0x3ad80100
	s_mov_b64 s[72:73], 0x3ada0100
	s_mov_b64 s[74:75], 0x8000100
	s_mov_b64 s[76:77], 0x8020100
	s_movk_i32 s97, 0x84
	s_mov_b32 s78, 0x3fd744fd
	s_mov_b64 s[80:81], 0x10000
	s_mov_b32 s82, 0x3a800000
	s_mov_b32 s83, 0x800000
	v_mov_b32_e32 v141, 0x200
	v_mov_b32_e32 v146, 0x400
	v_mov_b32_e32 v147, 0x600
	v_mov_b32_e32 v148, 0x800
	v_mov_b32_e32 v149, 0xa00
	v_mov_b32_e32 v150, 0xc00
	v_mov_b32_e32 v151, 0xe00
	v_writelane_b32 v225, s1, 19
